# same thresholded running-max update in the sample-attention tile loop as well
# speedup vs baseline: 1.0440x; 1.0049x over previous
; #define MFMA32(a, b, c) __builtin_amdgcn_mfma_f32_32x32x16_bf16((a), (b), (c), 0, 0, 0)
;     ...
;     auto compute = [&](const bf16_t* Kt, const bf16_t* Vt, int t) {
;         f32x16 s0, s1;
; #pragma unroll
;         for (int i = 0; i < 16; ++i) { s0[i] = 0.f; s1[i] = 0.f; }
; #pragma unroll
;         for (int ks = 0; ks < NKS; ++ks) { const bf16x8 a0 = *(const bf16x8*)(Kt + lr * KSTR + 16 * ks + 8 * hi), a1 = *(const bf16x8*)(Kt + (32 + lr) * KSTR + 16 * ks + 8 * hi);
;             bf16x8 qq;
;             if (QREG == 1) qq = qf[ks];
;             else if (QREG == 2) qq = 16 * ks < DN ? qf[ks < NQF ? ks : 0] : *(const bf16x8*)(qr_row + (16 * ks - DN) + 8 * hi);
;             else qq = 16 * ks < DN ? *(const bf16x8*)(qa_row + 16 * ks + 8 * hi) : qf[(16 * ks - DN) / 16 < NQF ? (16 * ks - DN) / 16 : 0];
;             s0 = MFMA32(a0, qq, s0); s1 = MFMA32(a1, qq, s1);
;             if ((ks & 3) == 3) __builtin_amdgcn_sched_barrier(0); }
.Lsa_join:
	s_waitcnt lgkmcnt(0)
	s_barrier
	ds_read_b128 v[2:5], v217
	s_waitcnt vmcnt(15) lgkmcnt(0)
	v_mfma_f32_32x32x16_bf16 v[80:95], v[2:5], v[112:115], 0
	ds_read_b128 v[2:5], v217 offset:20992
	s_waitcnt lgkmcnt(0)
	v_mfma_f32_32x32x16_bf16 v[96:111], v[2:5], v[112:115], 0
	ds_read_b128 v[2:5], v217 offset:32
	s_waitcnt vmcnt(14) lgkmcnt(0)
	v_mfma_f32_32x32x16_bf16 v[80:95], v[2:5], v[116:119], v[80:95]
	ds_read_b128 v[2:5], v217 offset:21024
	s_waitcnt lgkmcnt(0)
	v_mfma_f32_32x32x16_bf16 v[96:111], v[2:5], v[116:119], v[96:111]
	ds_read_b128 v[2:5], v217 offset:64
	s_waitcnt vmcnt(13) lgkmcnt(0)
	v_mfma_f32_32x32x16_bf16 v[80:95], v[2:5], v[120:123], v[80:95]
	ds_read_b128 v[2:5], v217 offset:21056
	s_waitcnt lgkmcnt(0)
	v_mfma_f32_32x32x16_bf16 v[96:111], v[2:5], v[120:123], v[96:111]
	ds_read_b128 v[2:5], v217 offset:96
	s_waitcnt vmcnt(12) lgkmcnt(0)
	v_mfma_f32_32x32x16_bf16 v[80:95], v[2:5], v[124:127], v[80:95]
	ds_read_b128 v[2:5], v217 offset:21088
	s_waitcnt lgkmcnt(0)
	v_mfma_f32_32x32x16_bf16 v[96:111], v[2:5], v[124:127], v[96:111]
	ds_read_b128 v[2:5], v217 offset:128
	s_waitcnt vmcnt(11) lgkmcnt(0)
	v_mfma_f32_32x32x16_bf16 v[80:95], v[2:5], v[128:131], v[80:95]
	ds_read_b128 v[2:5], v217 offset:21120
	s_waitcnt lgkmcnt(0)
	v_mfma_f32_32x32x16_bf16 v[96:111], v[2:5], v[128:131], v[96:111]
	ds_read_b128 v[2:5], v217 offset:160
	s_waitcnt vmcnt(10) lgkmcnt(0)
	v_mfma_f32_32x32x16_bf16 v[80:95], v[2:5], v[132:135], v[80:95]
	ds_read_b128 v[2:5], v217 offset:21152
	s_waitcnt lgkmcnt(0)
	v_mfma_f32_32x32x16_bf16 v[96:111], v[2:5], v[132:135], v[96:111]
	ds_read_b128 v[2:5], v217 offset:192
	s_waitcnt vmcnt(9) lgkmcnt(0)
	v_mfma_f32_32x32x16_bf16 v[80:95], v[2:5], v[136:139], v[80:95]
	ds_read_b128 v[2:5], v217 offset:21184
	s_waitcnt lgkmcnt(0)
	v_mfma_f32_32x32x16_bf16 v[96:111], v[2:5], v[136:139], v[96:111]
	ds_read_b128 v[2:5], v217 offset:224
	s_waitcnt vmcnt(8) lgkmcnt(0)
	v_mfma_f32_32x32x16_bf16 v[80:95], v[2:5], v[140:143], v[80:95]
	ds_read_b128 v[2:5], v217 offset:21216
	s_waitcnt lgkmcnt(0)
	v_mfma_f32_32x32x16_bf16 v[96:111], v[2:5], v[140:143], v[96:111]
	ds_read_b128 v[2:5], v217 offset:256
	s_waitcnt vmcnt(7) lgkmcnt(0)
	v_mfma_f32_32x32x16_bf16 v[80:95], v[2:5], v[144:147], v[80:95]
	ds_read_b128 v[2:5], v217 offset:21248
	s_waitcnt lgkmcnt(0)
	v_mfma_f32_32x32x16_bf16 v[96:111], v[2:5], v[144:147], v[96:111]
	ds_read_b128 v[2:5], v217 offset:288
	s_waitcnt vmcnt(6) lgkmcnt(0)
	v_mfma_f32_32x32x16_bf16 v[80:95], v[2:5], v[148:151], v[80:95]
	ds_read_b128 v[2:5], v217 offset:21280
	s_waitcnt lgkmcnt(0)
	v_mfma_f32_32x32x16_bf16 v[96:111], v[2:5], v[148:151], v[96:111]
	ds_read_b128 v[2:5], v217 offset:320
	s_waitcnt vmcnt(5) lgkmcnt(0)
	v_mfma_f32_32x32x16_bf16 v[80:95], v[2:5], v[152:155], v[80:95]
	ds_read_b128 v[2:5], v217 offset:21312
	s_waitcnt lgkmcnt(0)
	v_mfma_f32_32x32x16_bf16 v[96:111], v[2:5], v[152:155], v[96:111]
	ds_read_b128 v[2:5], v217 offset:352
	s_waitcnt vmcnt(4) lgkmcnt(0)
	v_mfma_f32_32x32x16_bf16 v[80:95], v[2:5], v[156:159], v[80:95]
	ds_read_b128 v[2:5], v217 offset:21344
	s_waitcnt lgkmcnt(0)
	v_mfma_f32_32x32x16_bf16 v[96:111], v[2:5], v[156:159], v[96:111]
	ds_read_b128 v[2:5], v217 offset:384
	s_waitcnt vmcnt(3) lgkmcnt(0)
	v_mfma_f32_32x32x16_bf16 v[80:95], v[2:5], v[160:163], v[80:95]
	ds_read_b128 v[2:5], v217 offset:21376
	s_waitcnt lgkmcnt(0)
	v_mfma_f32_32x32x16_bf16 v[96:111], v[2:5], v[160:163], v[96:111]
	ds_read_b128 v[2:5], v217 offset:416
	s_waitcnt vmcnt(2) lgkmcnt(0)
	v_mfma_f32_32x32x16_bf16 v[80:95], v[2:5], v[164:167], v[80:95]
	ds_read_b128 v[2:5], v217 offset:21408
	s_waitcnt lgkmcnt(0)
	v_mfma_f32_32x32x16_bf16 v[96:111], v[2:5], v[164:167], v[96:111]
	ds_read_b128 v[2:5], v217 offset:448
	s_waitcnt vmcnt(1) lgkmcnt(0)
	v_mfma_f32_32x32x16_bf16 v[80:95], v[2:5], v[168:171], v[80:95]
	ds_read_b128 v[2:5], v217 offset:21440
	s_waitcnt lgkmcnt(0)
	v_mfma_f32_32x32x16_bf16 v[96:111], v[2:5], v[168:171], v[96:111]
	ds_read_b128 v[2:5], v217 offset:480
	s_waitcnt vmcnt(0) lgkmcnt(0)
	v_mfma_f32_32x32x16_bf16 v[80:95], v[2:5], v[172:175], v[80:95]
	ds_read_b128 v[2:5], v217 offset:21472
	s_waitcnt lgkmcnt(0)
	v_mfma_f32_32x32x16_bf16 v[96:111], v[2:5], v[172:175], v[96:111]
	global_load_dwordx4 v[6:9], v[178:179], off offset:256
	ds_read_b128 v[2:5], v217 offset:21504
	ds_read_b128 v[10:13], v217 offset:512
	ds_read_b128 v[242:245], v217 offset:544
	s_waitcnt vmcnt(0) lgkmcnt(1)
	v_mfma_f32_32x32x16_bf16 v[80:95], v[10:13], v[6:9], v[80:95]
	v_mfma_f32_32x32x16_bf16 v[96:111], v[2:5], v[6:9], v[96:111]
	global_load_dwordx4 v[6:9], v[178:179], off offset:288
	ds_read_b128 v[2:5], v217 offset:21536
	s_waitcnt vmcnt(0) lgkmcnt(1)
; #define MFMA32(a, b, c) __builtin_amdgcn_mfma_f32_32x32x16_bf16((a), (b), (c), 0, 0, 0)
; DI float xhalf_max(float v) { const auto r = __builtin_amdgcn_permlane32_swap(__float_as_uint(v), __float_as_uint(v), false, false); return fmaxf(__uint_as_float(r[0]), __uint_as_float(r[1])); }
;     ...
;         for (int ks = 0; ks < NKS; ++ks) { const bf16x8 a0 = *(const bf16x8*)(Kt + lr * KSTR + 16 * ks + 8 * hi), a1 = *(const bf16x8*)(Kt + (32 + lr) * KSTR + 16 * ks + 8 * hi);
;             bf16x8 qq;
;             if (QREG == 1) qq = qf[ks];
;             else if (QREG == 2) qq = 16 * ks < DN ? qf[ks < NQF ? ks : 0] : *(const bf16x8*)(qr_row + (16 * ks - DN) + 8 * hi);
;             else qq = 16 * ks < DN ? *(const bf16x8*)(qa_row + 16 * ks + 8 * hi) : qf[(16 * ks - DN) / 16 < NQF ? (16 * ks - DN) / 16 : 0];
;             s0 = MFMA32(a0, qq, s0); s1 = MFMA32(a1, qq, s1);
;             if ((ks & 3) == 3) __builtin_amdgcn_sched_barrier(0); }
;         if (t == 0) {
; #pragma unroll
;             for (int i = 0; i < 16; ++i) { if (i >= 8) s0[i] = -INFINITY; s1[i] = -INFINITY; } }
;         float mx = s0[0];
; #pragma unroll
;         for (int i = 1; i < 16; ++i) mx = fmaxf(mx, s0[i]);
; #pragma unroll
;         for (int i = 0; i < 16; ++i) mx = fmaxf(mx, s1[i]);
;         mx = xhalf_max(mx);
;         const float mnew = fmaxf(mrun, mx), alpha = __builtin_amdgcn_exp2f(mrun - mnew);
;         const bool resc = __builtin_amdgcn_ballot_w64(mnew != mrun) != 0ull; mrun = mnew;
;         float ps = 0.f;
; #pragma unroll
;         for (int i = 0; i < 16; ++i) { s0[i] = __builtin_amdgcn_exp2f(s0[i] - mnew); s1[i] = __builtin_amdgcn_exp2f(s1[i] - mnew); ps += s0[i] + s1[i]; }
;         lrun = lrun * alpha + ps;
;         if (resc) {
; #pragma unroll
;             for (int d = 0; d < 4; ++d)
; #pragma unroll
;                 for (int i = 0; i < 16; ++i) oacc[d][i] *= alpha; }
	v_mfma_f32_32x32x16_bf16 v[80:95], v[242:245], v[6:9], v[80:95]
	s_waitcnt lgkmcnt(0)
	v_mfma_f32_32x32x16_bf16 v[96:111], v[2:5], v[6:9], v[96:111]
	ds_read_b128 v[2:5], v217 offset:576
	ds_read_b128 v[6:9], v217 offset:21568
	global_load_dwordx4 v[10:13], v[178:179], off offset:320
	s_waitcnt vmcnt(0) lgkmcnt(1)
	v_mfma_f32_32x32x16_bf16 v[80:95], v[2:5], v[10:13], v[80:95]
	s_waitcnt lgkmcnt(0)
	v_mfma_f32_32x32x16_bf16 v[96:111], v[6:9], v[10:13], v[96:111]
	ds_read_b128 v[2:5], v217 offset:608
	ds_read_b128 v[6:9], v217 offset:21600
	global_load_dwordx4 v[10:13], v[178:179], off offset:352
	s_waitcnt vmcnt(0) lgkmcnt(1)
	v_mfma_f32_32x32x16_bf16 v[80:95], v[2:5], v[10:13], v[80:95]
	s_waitcnt lgkmcnt(0)
	v_mfma_f32_32x32x16_bf16 v[96:111], v[6:9], v[10:13], v[96:111]
	s_nop 9
	v_max_f32_e32 v0, v81, v81
	v_max_f32_e32 v2, v80, v80
	v_max_f32_e32 v0, v2, v0
	v_max3_f32 v0, v0, v82, v83
	v_max3_f32 v0, v0, v84, v85
	v_cndmask_b32_e64 v88, v88, v215, s[16:17]
	v_cndmask_b32_e64 v15, v89, v215, s[16:17]
	v_max3_f32 v0, v0, v86, v87
	v_cndmask_b32_e64 v12, v90, v215, s[16:17]
	v_cndmask_b32_e64 v11, v91, v215, s[16:17]
	v_max3_f32 v0, v0, v88, v15
	v_cndmask_b32_e64 v8, v92, v215, s[16:17]
	v_cndmask_b32_e64 v7, v93, v215, s[16:17]
	v_max3_f32 v0, v0, v12, v11
	v_cndmask_b32_e64 v5, v94, v215, s[16:17]
	v_cndmask_b32_e64 v4, v95, v215, s[16:17]
	v_max3_f32 v0, v0, v8, v7
	v_cndmask_b32_e64 v95, v99, v215, s[16:17]
	v_cndmask_b32_e64 v99, v96, v215, s[16:17]
	v_cndmask_b32_e64 v96, v97, v215, s[16:17]
	v_max3_f32 v0, v0, v5, v4
	v_cndmask_b32_e64 v98, v98, v215, s[16:17]
	v_max3_f32 v0, v0, v99, v96
	v_cndmask_b32_e64 v94, v100, v215, s[16:17]
	v_cndmask_b32_e64 v93, v101, v215, s[16:17]
	v_max3_f32 v0, v0, v98, v95
	v_cndmask_b32_e64 v92, v102, v215, s[16:17]
	v_cndmask_b32_e64 v91, v103, v215, s[16:17]
	v_max3_f32 v0, v0, v94, v93
	v_cndmask_b32_e64 v90, v104, v215, s[16:17]
	v_cndmask_b32_e64 v89, v105, v215, s[16:17]
	v_max3_f32 v0, v0, v92, v91
	v_cndmask_b32_e64 v14, v106, v215, s[16:17]
	v_cndmask_b32_e64 v13, v107, v215, s[16:17]
	v_max3_f32 v0, v0, v90, v89
	v_cndmask_b32_e64 v10, v108, v215, s[16:17]
	v_cndmask_b32_e64 v9, v109, v215, s[16:17]
	v_max3_f32 v0, v0, v14, v13
	v_cndmask_b32_e64 v6, v110, v215, s[16:17]
	v_cndmask_b32_e64 v3, v111, v215, s[16:17]
	v_max3_f32 v0, v0, v10, v9
	v_max3_f32 v0, v0, v6, v3
	v_mov_b32_e32 v2, v0
	s_nop 1
	v_permlane32_swap_b32_e32 v0, v2
	v_max3_f32 v2, v240, v0, v2
	v_sub_f32_e32 v0, v2, v240
	v_cmp_lt_f32_e32 vcc, 0x41000000, v0
	v_cndmask_b32_e32 v2, v240, v2, vcc
	v_sub_f32_e32 v0, v240, v2
	v_exp_f32_e32 v0, v0
	v_cmp_neq_f32_e32 vcc, v2, v240
	s_cbranch_vccz .LBB0_1976
	v_pk_mul_f32 v[78:79], v[78:79], v[0:1] op_sel_hi:[1,0]
	v_pk_mul_f32 v[76:77], v[76:77], v[0:1] op_sel_hi:[1,0]
	v_pk_mul_f32 v[74:75], v[74:75], v[0:1] op_sel_hi:[1,0]
	v_pk_mul_f32 v[72:73], v[72:73], v[0:1] op_sel_hi:[1,0]
	v_pk_mul_f32 v[70:71], v[70:71], v[0:1] op_sel_hi:[1,0]
	v_pk_mul_f32 v[68:69], v[68:69], v[0:1] op_sel_hi:[1,0]
	v_pk_mul_f32 v[66:67], v[66:67], v[0:1] op_sel_hi:[1,0]
	v_pk_mul_f32 v[64:65], v[64:65], v[0:1] op_sel_hi:[1,0]
	v_pk_mul_f32 v[62:63], v[62:63], v[0:1] op_sel_hi:[1,0]
	v_pk_mul_f32 v[60:61], v[60:61], v[0:1] op_sel_hi:[1,0]
	v_pk_mul_f32 v[58:59], v[58:59], v[0:1] op_sel_hi:[1,0]
	v_pk_mul_f32 v[56:57], v[56:57], v[0:1] op_sel_hi:[1,0]
	v_pk_mul_f32 v[54:55], v[54:55], v[0:1] op_sel_hi:[1,0]
	v_pk_mul_f32 v[52:53], v[52:53], v[0:1] op_sel_hi:[1,0]
	v_pk_mul_f32 v[50:51], v[50:51], v[0:1] op_sel_hi:[1,0]
	v_pk_mul_f32 v[48:49], v[48:49], v[0:1] op_sel_hi:[1,0]
	v_pk_mul_f32 v[46:47], v[46:47], v[0:1] op_sel_hi:[1,0]
	v_pk_mul_f32 v[44:45], v[44:45], v[0:1] op_sel_hi:[1,0]
	v_pk_mul_f32 v[42:43], v[42:43], v[0:1] op_sel_hi:[1,0]
	v_pk_mul_f32 v[40:41], v[40:41], v[0:1] op_sel_hi:[1,0]
	v_pk_mul_f32 v[38:39], v[38:39], v[0:1] op_sel_hi:[1,0]
	v_pk_mul_f32 v[36:37], v[36:37], v[0:1] op_sel_hi:[1,0]
	v_pk_mul_f32 v[34:35], v[34:35], v[0:1] op_sel_hi:[1,0]
	v_pk_mul_f32 v[32:33], v[32:33], v[0:1] op_sel_hi:[1,0]
	v_pk_mul_f32 v[30:31], v[30:31], v[0:1] op_sel_hi:[1,0]
	v_pk_mul_f32 v[28:29], v[28:29], v[0:1] op_sel_hi:[1,0]
	v_pk_mul_f32 v[26:27], v[26:27], v[0:1] op_sel_hi:[1,0]
	v_pk_mul_f32 v[24:25], v[24:25], v[0:1] op_sel_hi:[1,0]
	v_pk_mul_f32 v[22:23], v[22:23], v[0:1] op_sel_hi:[1,0]
	v_pk_mul_f32 v[20:21], v[20:21], v[0:1] op_sel_hi:[1,0]
	v_pk_mul_f32 v[18:19], v[18:19], v[0:1] op_sel_hi:[1,0]
	v_pk_mul_f32 v[16:17], v[16:17], v[0:1] op_sel_hi:[1,0]
